# fastdiv version with the four hottest GEMM inner loops aligned to 64 bytes (code placement test)
# baseline (speedup 1.0000x reference)
; template <class Epi, class Sched>
; DI void gemm_phase(LAS unsigned char* lds, const Gemm g, const Sched& S, const Epi& E) {
;     ...
;     Unit cur, nxt; int ui = 0;
;     if (!S.next(0, cur)) return;
;     f32x4 acc[2][2][4][2];
; #pragma unroll
;     for (int a = 0; a < 2; ++a)
; #pragma unroll
;         for (int b = 0; b < 2; ++b)
; #pragma unroll
;             for (int m = 0; m < 4; ++m)
; #pragma unroll
;                 for (int n = 0; n < 2; ++n) acc[a][b][m][n] = (f32x4){0.f, 0.f, 0.f, 0.f};
;     bf16x8 At[4][2], B0[2][2], B1[2][2];
;     const char* cA = (const char*)g.A + (size_t)cur.pm * tstepA; const char* cB = (const char*)g.Bt + (size_t)cur.pn * tstepB;
.LBB0_29:
	s_add_u32 s60, s2, 0x100
	v_mov_b32_e32 v4, 0
	s_addc_u32 s61, s3, 0
	s_mov_b32 s64, -2
	v_mov_b32_e32 v5, v4
	v_mov_b32_e32 v6, v4
	v_mov_b32_e32 v7, v4
	v_mov_b32_e32 v8, v4
	v_mov_b32_e32 v9, v4
	v_mov_b32_e32 v10, v4
	v_mov_b32_e32 v11, v4
	v_mov_b32_e32 v12, v4
	v_mov_b32_e32 v13, v4
	v_mov_b32_e32 v14, v4
	v_mov_b32_e32 v15, v4
	v_mov_b32_e32 v20, v4
	v_mov_b32_e32 v21, v4
	v_mov_b32_e32 v22, v4
	v_mov_b32_e32 v23, v4
	v_mov_b32_e32 v28, v4
	v_mov_b32_e32 v29, v4
	v_mov_b32_e32 v30, v4
	v_mov_b32_e32 v31, v4
	v_mov_b32_e32 v36, v4
	v_mov_b32_e32 v37, v4
	v_mov_b32_e32 v38, v4
	v_mov_b32_e32 v39, v4
	v_mov_b32_e32 v44, v4
	v_mov_b32_e32 v45, v4
	v_mov_b32_e32 v46, v4
	v_mov_b32_e32 v47, v4
	v_mov_b32_e32 v52, v4
	v_mov_b32_e32 v53, v4
	v_mov_b32_e32 v54, v4
	v_mov_b32_e32 v55, v4
	v_mov_b32_e32 v16, v4
	v_mov_b32_e32 v17, v4
	v_mov_b32_e32 v18, v4
	v_mov_b32_e32 v19, v4
	v_mov_b32_e32 v24, v4
	v_mov_b32_e32 v25, v4
	v_mov_b32_e32 v26, v4
	v_mov_b32_e32 v27, v4
	v_mov_b32_e32 v32, v4
	v_mov_b32_e32 v33, v4
	v_mov_b32_e32 v34, v4
	v_mov_b32_e32 v35, v4
	v_mov_b32_e32 v40, v4
	v_mov_b32_e32 v41, v4
	v_mov_b32_e32 v42, v4
	v_mov_b32_e32 v43, v4
	v_mov_b32_e32 v48, v4
	v_mov_b32_e32 v49, v4
	v_mov_b32_e32 v50, v4
	v_mov_b32_e32 v51, v4
	v_mov_b32_e32 v56, v4
	v_mov_b32_e32 v57, v4
	v_mov_b32_e32 v58, v4
	v_mov_b32_e32 v59, v4
	v_mov_b32_e32 v60, v4
	v_mov_b32_e32 v61, v4
	v_mov_b32_e32 v62, v4
	v_mov_b32_e32 v63, v4
	v_mov_b32_e32 v64, v4
	v_mov_b32_e32 v65, v4
	v_mov_b32_e32 v66, v4
	v_mov_b32_e32 v67, v4
	v_mov_b32_e32 v68, v4
	v_mov_b32_e32 v69, v4
	v_mov_b32_e32 v70, v4
	v_mov_b32_e32 v71, v4
	v_mov_b32_e32 v72, v4
	v_mov_b32_e32 v73, v4
	v_mov_b32_e32 v74, v4
	v_mov_b32_e32 v75, v4
	v_mov_b32_e32 v84, v4
	v_mov_b32_e32 v85, v4
	v_mov_b32_e32 v86, v4
	v_mov_b32_e32 v87, v4
	v_mov_b32_e32 v88, v4
	v_mov_b32_e32 v89, v4
	v_mov_b32_e32 v90, v4
	v_mov_b32_e32 v91, v4
	v_mov_b32_e32 v100, v4
	v_mov_b32_e32 v101, v4
	v_mov_b32_e32 v102, v4
	v_mov_b32_e32 v103, v4
	v_mov_b32_e32 v104, v4
	v_mov_b32_e32 v105, v4
	v_mov_b32_e32 v106, v4
	v_mov_b32_e32 v107, v4
	v_mov_b32_e32 v132, v4
	v_mov_b32_e32 v133, v4
	v_mov_b32_e32 v134, v4
	v_mov_b32_e32 v135, v4
	v_mov_b32_e32 v136, v4
	v_mov_b32_e32 v137, v4
	v_mov_b32_e32 v138, v4
	v_mov_b32_e32 v139, v4
	v_mov_b32_e32 v76, v4
	v_mov_b32_e32 v77, v4
	v_mov_b32_e32 v78, v4
	v_mov_b32_e32 v79, v4
	v_mov_b32_e32 v80, v4
	v_mov_b32_e32 v81, v4
	v_mov_b32_e32 v82, v4
	v_mov_b32_e32 v83, v4
	v_mov_b32_e32 v92, v4
	v_mov_b32_e32 v93, v4
	v_mov_b32_e32 v94, v4
	v_mov_b32_e32 v95, v4
	v_mov_b32_e32 v96, v4
	v_mov_b32_e32 v97, v4
	v_mov_b32_e32 v98, v4
	v_mov_b32_e32 v99, v4
	v_mov_b32_e32 v120, v4
	v_mov_b32_e32 v121, v4
	v_mov_b32_e32 v122, v4
	v_mov_b32_e32 v123, v4
	v_mov_b32_e32 v124, v4
	v_mov_b32_e32 v125, v4
	v_mov_b32_e32 v126, v4
	v_mov_b32_e32 v127, v4
	v_mov_b32_e32 v140, v4
	v_mov_b32_e32 v141, v4
	v_mov_b32_e32 v142, v4
	v_mov_b32_e32 v143, v4
	v_mov_b32_e32 v144, v4
	v_mov_b32_e32 v145, v4
	v_mov_b32_e32 v146, v4
	v_mov_b32_e32 v147, v4
	.p2align	6

; template <class Epi, class Sched>
; DI void gemm_phase(LAS unsigned char* lds, const Gemm g, const Sched& S, const Epi& E) {
;     ...
;         const bool has_next = S.next(ui + 1, nxt);
;         const char* nA = has_next ? (const char*)g.A + (size_t)nxt.pm * tstepA : cA; const char* nB = has_next ? (const char*)g.Bt + (size_t)nxt.pn * tstepB : cB;
;         for (int t = 0; t < nt; t += 2) {
;             const bool last = (t == nt - 2);
;             const char* a1 = cA + (size_t)(t + 1) * kstep;
;             const char* a2 = last ? nA : cA + (size_t)(t + 2) * kstep; const char* b2 = last ? nB : cB + (size_t)(t + 2) * kstep;
;             const char* a3 = a2 + kstep; const char* b3 = b2 + kstep;
;     ...
;         for (int a = 0; a < 2; ++a)
; #pragma unroll
;             for (int b = 0; b < 2; ++b)
; #pragma unroll
;                 for (int m = 0; m < 4; ++m)
; #pragma unroll
;                     for (int n = 0; n < 2; ++n) acc[a][b][m][n] = (f32x4){0.f, 0.f, 0.f, 0.f};
;         cur = nxt; cA = nA; cB = nB; ++ui;
.LBB0_46:
	v_mov_b64_e32 v[4:5], 0xb00
	s_ashr_i32 s31, s30, 31
	v_cmp_lt_i64_e32 vcc, s[34:35], v[4:5]
	s_lshl_b64 s[34:35], s[30:31], 20
	s_add_u32 s34, s4, s34
	s_addc_u32 s35, s5, s35
	s_and_b64 s[36:37], vcc, exec
	s_cselect_b32 s31, s35, s21
	s_cselect_b32 s59, s34, s20
	s_ashr_i32 s27, s26, 31
	s_lshl_b64 s[36:37], s[26:27], 20
	s_add_u32 s36, s43, s36
	s_addc_u32 s37, s44, s37
	s_and_b64 s[38:39], vcc, exec
	s_cselect_b32 s27, s37, s3
	s_cselect_b32 s60, s36, s2
	s_add_u32 s20, s20, 0x80080
	s_addc_u32 s21, s21, 0
	s_add_u32 s61, s2, 0x100
	v_mov_b32_e32 v4, 0
	s_addc_u32 s64, s3, 0
	s_mov_b32 s65, -2
	v_mov_b32_e32 v5, v4
	v_mov_b32_e32 v6, v4
	v_mov_b32_e32 v7, v4
	v_mov_b32_e32 v12, v4
	v_mov_b32_e32 v13, v4
	v_mov_b32_e32 v14, v4
	v_mov_b32_e32 v15, v4
	v_mov_b32_e32 v20, v4
	v_mov_b32_e32 v21, v4
	v_mov_b32_e32 v22, v4
	v_mov_b32_e32 v23, v4
	v_mov_b32_e32 v28, v4
	v_mov_b32_e32 v29, v4
	v_mov_b32_e32 v30, v4
	v_mov_b32_e32 v31, v4
	v_mov_b32_e32 v36, v4
	v_mov_b32_e32 v37, v4
	v_mov_b32_e32 v38, v4
	v_mov_b32_e32 v39, v4
	v_mov_b32_e32 v44, v4
	v_mov_b32_e32 v45, v4
	v_mov_b32_e32 v46, v4
	v_mov_b32_e32 v47, v4
	v_mov_b32_e32 v52, v4
	v_mov_b32_e32 v53, v4
	v_mov_b32_e32 v54, v4
	v_mov_b32_e32 v55, v4
	v_mov_b32_e32 v60, v4
	v_mov_b32_e32 v61, v4
	v_mov_b32_e32 v62, v4
	v_mov_b32_e32 v63, v4
	v_mov_b32_e32 v8, v4
	v_mov_b32_e32 v9, v4
	v_mov_b32_e32 v10, v4
	v_mov_b32_e32 v11, v4
	v_mov_b32_e32 v16, v4
	v_mov_b32_e32 v17, v4
	v_mov_b32_e32 v18, v4
	v_mov_b32_e32 v19, v4
	v_mov_b32_e32 v24, v4
	v_mov_b32_e32 v25, v4
	v_mov_b32_e32 v26, v4
	v_mov_b32_e32 v27, v4
	v_mov_b32_e32 v32, v4
	v_mov_b32_e32 v33, v4
	v_mov_b32_e32 v34, v4
	v_mov_b32_e32 v35, v4
	v_mov_b32_e32 v40, v4
	v_mov_b32_e32 v41, v4
	v_mov_b32_e32 v42, v4
	v_mov_b32_e32 v43, v4
	v_mov_b32_e32 v48, v4
	v_mov_b32_e32 v49, v4
	v_mov_b32_e32 v50, v4
	v_mov_b32_e32 v51, v4
	v_mov_b32_e32 v56, v4
	v_mov_b32_e32 v57, v4
	v_mov_b32_e32 v58, v4
	v_mov_b32_e32 v59, v4
	v_mov_b32_e32 v64, v4
	v_mov_b32_e32 v65, v4
	v_mov_b32_e32 v66, v4
	v_mov_b32_e32 v67, v4
	v_mov_b32_e32 v68, v4
	v_mov_b32_e32 v69, v4
	v_mov_b32_e32 v70, v4
	v_mov_b32_e32 v71, v4
	v_mov_b32_e32 v76, v4
	v_mov_b32_e32 v77, v4
	v_mov_b32_e32 v78, v4
	v_mov_b32_e32 v79, v4
	v_mov_b32_e32 v84, v4
	v_mov_b32_e32 v85, v4
	v_mov_b32_e32 v86, v4
	v_mov_b32_e32 v87, v4
	v_mov_b32_e32 v92, v4
	v_mov_b32_e32 v93, v4
	v_mov_b32_e32 v94, v4
	v_mov_b32_e32 v95, v4
	v_mov_b32_e32 v100, v4
	v_mov_b32_e32 v101, v4
	v_mov_b32_e32 v102, v4
	v_mov_b32_e32 v103, v4
	v_mov_b32_e32 v108, v4
	v_mov_b32_e32 v109, v4
	v_mov_b32_e32 v110, v4
	v_mov_b32_e32 v111, v4
	v_mov_b32_e32 v116, v4
	v_mov_b32_e32 v117, v4
	v_mov_b32_e32 v118, v4
	v_mov_b32_e32 v119, v4
	v_mov_b32_e32 v124, v4
	v_mov_b32_e32 v125, v4
	v_mov_b32_e32 v126, v4
	v_mov_b32_e32 v127, v4
	v_mov_b32_e32 v72, v4
	v_mov_b32_e32 v73, v4
	v_mov_b32_e32 v74, v4
	v_mov_b32_e32 v75, v4
	v_mov_b32_e32 v80, v4
	v_mov_b32_e32 v81, v4
	v_mov_b32_e32 v82, v4
	v_mov_b32_e32 v83, v4
	v_mov_b32_e32 v88, v4
	v_mov_b32_e32 v89, v4
	v_mov_b32_e32 v90, v4
	v_mov_b32_e32 v91, v4
	v_mov_b32_e32 v96, v4
	v_mov_b32_e32 v97, v4
	v_mov_b32_e32 v98, v4
	v_mov_b32_e32 v99, v4
	v_mov_b32_e32 v104, v4
	v_mov_b32_e32 v105, v4
	v_mov_b32_e32 v106, v4
	v_mov_b32_e32 v107, v4
	v_mov_b32_e32 v112, v4
	v_mov_b32_e32 v113, v4
	v_mov_b32_e32 v114, v4
	v_mov_b32_e32 v115, v4
	v_mov_b32_e32 v120, v4
	v_mov_b32_e32 v121, v4
	v_mov_b32_e32 v122, v4
	v_mov_b32_e32 v123, v4
	v_mov_b32_e32 v128, v4
	v_mov_b32_e32 v129, v4
	v_mov_b32_e32 v130, v4
	v_mov_b32_e32 v131, v4
	.p2align	6

; template <class Epi, class Sched>
; DI void gemm_phase(LAS unsigned char* lds, const Gemm g, const Sched& S, const Epi& E) {
;     ...
;         const bool has_next = S.next(ui + 1, nxt);
;         const char* nA = has_next ? (const char*)g.A + (size_t)nxt.pm * tstepA : cA; const char* nB = has_next ? (const char*)g.Bt + (size_t)nxt.pn * tstepB : cB;
;         for (int t = 0; t < nt; t += 2) {
;             const bool last = (t == nt - 2);
;             const char* a1 = cA + (size_t)(t + 1) * kstep;
;             const char* a2 = last ? nA : cA + (size_t)(t + 2) * kstep; const char* b2 = last ? nB : cB + (size_t)(t + 2) * kstep;
;             const char* a3 = a2 + kstep; const char* b3 = b2 + kstep;
;     ...
;         for (int a = 0; a < 2; ++a)
; #pragma unroll
;             for (int b = 0; b < 2; ++b)
; #pragma unroll
;                 for (int m = 0; m < 4; ++m)
; #pragma unroll
;                     for (int n = 0; n < 2; ++n) acc[a][b][m][n] = (f32x4){0.f, 0.f, 0.f, 0.f};
;         cur = nxt; cA = nA; cB = nB; ++ui;
.LBB0_70:
	s_ashr_i32 s27, s26, 31
	v_cmp_lt_i64_e32 vcc, s[30:31], v[194:195]
	s_lshl_b64 s[30:31], s[26:27], 20
	s_add_u32 s30, s43, s30
	s_addc_u32 s31, s44, s31
	s_and_b64 s[34:35], vcc, exec
	s_cselect_b32 s27, s31, s37
	s_cselect_b32 s58, s30, s36
	s_ashr_i32 s25, s24, 31
	s_lshl_b64 s[34:35], s[24:25], 20
	s_add_u32 s34, s45, s34
	s_addc_u32 s35, s48, s35
	s_and_b64 s[38:39], vcc, exec
	s_cselect_b32 s25, s35, s3
	s_cselect_b32 s59, s34, s2
	s_add_u32 s36, s36, 0x80080
	s_addc_u32 s37, s37, 0
	s_add_u32 s60, s2, 0x100
	v_mov_b32_e32 v4, 0
	s_addc_u32 s61, s3, 0
	s_mov_b32 s64, -2
	v_mov_b32_e32 v5, v4
	v_mov_b32_e32 v6, v4
	v_mov_b32_e32 v7, v4
	v_mov_b32_e32 v8, v4
	v_mov_b32_e32 v9, v4
	v_mov_b32_e32 v10, v4
	v_mov_b32_e32 v11, v4
	v_mov_b32_e32 v12, v4
	v_mov_b32_e32 v13, v4
	v_mov_b32_e32 v14, v4
	v_mov_b32_e32 v15, v4
	v_mov_b32_e32 v20, v4
	v_mov_b32_e32 v21, v4
	v_mov_b32_e32 v22, v4
	v_mov_b32_e32 v23, v4
	v_mov_b32_e32 v28, v4
	v_mov_b32_e32 v29, v4
	v_mov_b32_e32 v30, v4
	v_mov_b32_e32 v31, v4
	v_mov_b32_e32 v36, v4
	v_mov_b32_e32 v37, v4
	v_mov_b32_e32 v38, v4
	v_mov_b32_e32 v39, v4
	v_mov_b32_e32 v44, v4
	v_mov_b32_e32 v45, v4
	v_mov_b32_e32 v46, v4
	v_mov_b32_e32 v47, v4
	v_mov_b32_e32 v52, v4
	v_mov_b32_e32 v53, v4
	v_mov_b32_e32 v54, v4
	v_mov_b32_e32 v55, v4
	v_mov_b32_e32 v16, v4
	v_mov_b32_e32 v17, v4
	v_mov_b32_e32 v18, v4
	v_mov_b32_e32 v19, v4
	v_mov_b32_e32 v24, v4
	v_mov_b32_e32 v25, v4
	v_mov_b32_e32 v26, v4
	v_mov_b32_e32 v27, v4
	v_mov_b32_e32 v32, v4
	v_mov_b32_e32 v33, v4
	v_mov_b32_e32 v34, v4
	v_mov_b32_e32 v35, v4
	v_mov_b32_e32 v40, v4
	v_mov_b32_e32 v41, v4
	v_mov_b32_e32 v42, v4
	v_mov_b32_e32 v43, v4
	v_mov_b32_e32 v48, v4
	v_mov_b32_e32 v49, v4
	v_mov_b32_e32 v50, v4
	v_mov_b32_e32 v51, v4
	v_mov_b32_e32 v56, v4
	v_mov_b32_e32 v57, v4
	v_mov_b32_e32 v58, v4
	v_mov_b32_e32 v59, v4
	v_mov_b32_e32 v60, v4
	v_mov_b32_e32 v61, v4
	v_mov_b32_e32 v62, v4
	v_mov_b32_e32 v63, v4
	v_mov_b32_e32 v64, v4
	v_mov_b32_e32 v65, v4
	v_mov_b32_e32 v66, v4
	v_mov_b32_e32 v67, v4
	v_mov_b32_e32 v68, v4
	v_mov_b32_e32 v69, v4
	v_mov_b32_e32 v70, v4
	v_mov_b32_e32 v71, v4
	v_mov_b32_e32 v72, v4
	v_mov_b32_e32 v73, v4
	v_mov_b32_e32 v74, v4
	v_mov_b32_e32 v75, v4
	v_mov_b32_e32 v84, v4
	v_mov_b32_e32 v85, v4
	v_mov_b32_e32 v86, v4
	v_mov_b32_e32 v87, v4
	v_mov_b32_e32 v88, v4
	v_mov_b32_e32 v89, v4
	v_mov_b32_e32 v90, v4
	v_mov_b32_e32 v91, v4
	v_mov_b32_e32 v100, v4
	v_mov_b32_e32 v101, v4
	v_mov_b32_e32 v102, v4
	v_mov_b32_e32 v103, v4
	v_mov_b32_e32 v104, v4
	v_mov_b32_e32 v105, v4
	v_mov_b32_e32 v106, v4
	v_mov_b32_e32 v107, v4
	v_mov_b32_e32 v132, v4
	v_mov_b32_e32 v133, v4
	v_mov_b32_e32 v134, v4
	v_mov_b32_e32 v135, v4
	v_mov_b32_e32 v136, v4
	v_mov_b32_e32 v137, v4
	v_mov_b32_e32 v138, v4
	v_mov_b32_e32 v139, v4
	v_mov_b32_e32 v76, v4
	v_mov_b32_e32 v77, v4
	v_mov_b32_e32 v78, v4
	v_mov_b32_e32 v79, v4
	v_mov_b32_e32 v80, v4
	v_mov_b32_e32 v81, v4
	v_mov_b32_e32 v82, v4
	v_mov_b32_e32 v83, v4
	v_mov_b32_e32 v92, v4
	v_mov_b32_e32 v93, v4
	v_mov_b32_e32 v94, v4
	v_mov_b32_e32 v95, v4
	v_mov_b32_e32 v96, v4
	v_mov_b32_e32 v97, v4
	v_mov_b32_e32 v98, v4
	v_mov_b32_e32 v99, v4
	v_mov_b32_e32 v116, v4
	v_mov_b32_e32 v117, v4
	v_mov_b32_e32 v118, v4
	v_mov_b32_e32 v119, v4
	v_mov_b32_e32 v124, v4
	v_mov_b32_e32 v125, v4
	v_mov_b32_e32 v126, v4
	v_mov_b32_e32 v127, v4
	v_mov_b32_e32 v140, v4
	v_mov_b32_e32 v141, v4
	v_mov_b32_e32 v142, v4
	v_mov_b32_e32 v143, v4
	v_mov_b32_e32 v144, v4
	v_mov_b32_e32 v145, v4
	v_mov_b32_e32 v146, v4
	v_mov_b32_e32 v147, v4
	.p2align	6

; template <class Epi, class Sched>
; DI void gemm_phase(LAS unsigned char* lds, const Gemm g, const Sched& S, const Epi& E) {
;     ...
;         const bool has_next = S.next(ui + 1, nxt);
;         const char* nA = has_next ? (const char*)g.A + (size_t)nxt.pm * tstepA : cA; const char* nB = has_next ? (const char*)g.Bt + (size_t)nxt.pn * tstepB : cB;
;         for (int t = 0; t < nt; t += 2) {
;             const bool last = (t == nt - 2);
;             const char* a1 = cA + (size_t)(t + 1) * kstep;
;             const char* a2 = last ? nA : cA + (size_t)(t + 2) * kstep; const char* b2 = last ? nB : cB + (size_t)(t + 2) * kstep;
;             const char* a3 = a2 + kstep; const char* b3 = b2 + kstep;
;     ...
;         for (int a = 0; a < 2; ++a)
; #pragma unroll
;             for (int b = 0; b < 2; ++b)
; #pragma unroll
;                 for (int m = 0; m < 4; ++m)
; #pragma unroll
;                     for (int n = 0; n < 2; ++n) acc[a][b][m][n] = (f32x4){0.f, 0.f, 0.f, 0.f};
;         cur = nxt; cA = nA; cB = nB; ++ui;
.LBB0_1207:
	s_ashr_i32 s37, s36, 31
	s_xor_b64 s[40:41], s[44:45], -1
	s_lshl_b64 s[38:39], s[36:37], 20
	s_add_u32 s38, s49, s38
	s_addc_u32 s39, s50, s39
	s_and_b64 s[42:43], s[44:45], exec
	s_cselect_b32 s37, s39, s21
	s_cselect_b32 s56, s38, s20
	s_ashr_i32 s35, s34, 31
	s_lshl_b64 s[42:43], s[34:35], 20
	s_add_u32 s42, s51, s42
	s_addc_u32 s43, s52, s43
	s_and_b64 s[44:45], s[44:45], exec
	s_cselect_b32 s35, s43, s3
	s_cselect_b32 s92, s42, s2
	s_add_u32 s20, s20, 0x80080
	s_addc_u32 s21, s21, 0
	s_add_u32 s93, s2, 0x100
	v_mov_b32_e32 v4, 0
	s_addc_u32 vcc_lo, s3, 0
	s_mov_b32 s2, 0
	v_mov_b32_e32 v5, v4
	v_mov_b32_e32 v6, v4
	v_mov_b32_e32 v7, v4
	v_mov_b32_e32 v8, v4
	v_mov_b32_e32 v9, v4
	v_mov_b32_e32 v10, v4
	v_mov_b32_e32 v11, v4
	v_mov_b32_e32 v12, v4
	v_mov_b32_e32 v13, v4
	v_mov_b32_e32 v14, v4
	v_mov_b32_e32 v15, v4
	v_mov_b32_e32 v16, v4
	v_mov_b32_e32 v17, v4
	v_mov_b32_e32 v18, v4
	v_mov_b32_e32 v19, v4
	v_mov_b32_e32 v28, v4
	v_mov_b32_e32 v29, v4
	v_mov_b32_e32 v30, v4
	v_mov_b32_e32 v31, v4
	v_mov_b32_e32 v32, v4
	v_mov_b32_e32 v33, v4
	v_mov_b32_e32 v34, v4
	v_mov_b32_e32 v35, v4
	v_mov_b32_e32 v44, v4
	v_mov_b32_e32 v45, v4
	v_mov_b32_e32 v46, v4
	v_mov_b32_e32 v47, v4
	v_mov_b32_e32 v48, v4
	v_mov_b32_e32 v49, v4
	v_mov_b32_e32 v50, v4
	v_mov_b32_e32 v51, v4
	v_mov_b32_e32 v20, v4
	v_mov_b32_e32 v21, v4
	v_mov_b32_e32 v22, v4
	v_mov_b32_e32 v23, v4
	v_mov_b32_e32 v24, v4
	v_mov_b32_e32 v25, v4
	v_mov_b32_e32 v26, v4
	v_mov_b32_e32 v27, v4
	v_mov_b32_e32 v36, v4
	v_mov_b32_e32 v37, v4
	v_mov_b32_e32 v38, v4
	v_mov_b32_e32 v39, v4
	v_mov_b32_e32 v40, v4
	v_mov_b32_e32 v41, v4
	v_mov_b32_e32 v42, v4
	v_mov_b32_e32 v43, v4
	v_mov_b32_e32 v52, v4
	v_mov_b32_e32 v53, v4
	v_mov_b32_e32 v54, v4
	v_mov_b32_e32 v55, v4
	v_mov_b32_e32 v56, v4
	v_mov_b32_e32 v57, v4
	v_mov_b32_e32 v58, v4
	v_mov_b32_e32 v59, v4
	v_mov_b32_e32 v60, v4
	v_mov_b32_e32 v61, v4
	v_mov_b32_e32 v62, v4
	v_mov_b32_e32 v63, v4
	v_mov_b32_e32 v64, v4
	v_mov_b32_e32 v65, v4
	v_mov_b32_e32 v66, v4
	v_mov_b32_e32 v67, v4
	v_mov_b32_e32 v68, v4
	v_mov_b32_e32 v69, v4
	v_mov_b32_e32 v70, v4
	v_mov_b32_e32 v71, v4
	v_mov_b32_e32 v72, v4
	v_mov_b32_e32 v73, v4
	v_mov_b32_e32 v74, v4
	v_mov_b32_e32 v75, v4
	v_mov_b32_e32 v76, v4
	v_mov_b32_e32 v77, v4
	v_mov_b32_e32 v78, v4
	v_mov_b32_e32 v79, v4
	v_mov_b32_e32 v80, v4
	v_mov_b32_e32 v81, v4
	v_mov_b32_e32 v82, v4
	v_mov_b32_e32 v83, v4
	v_mov_b32_e32 v92, v4
	v_mov_b32_e32 v93, v4
	v_mov_b32_e32 v94, v4
	v_mov_b32_e32 v95, v4
	v_mov_b32_e32 v96, v4
	v_mov_b32_e32 v97, v4
	v_mov_b32_e32 v98, v4
	v_mov_b32_e32 v99, v4
	v_mov_b32_e32 v108, v4
	v_mov_b32_e32 v109, v4
	v_mov_b32_e32 v110, v4
	v_mov_b32_e32 v111, v4
	v_mov_b32_e32 v112, v4
	v_mov_b32_e32 v113, v4
	v_mov_b32_e32 v114, v4
	v_mov_b32_e32 v115, v4
	v_mov_b32_e32 v84, v4
	v_mov_b32_e32 v85, v4
	v_mov_b32_e32 v86, v4
	v_mov_b32_e32 v87, v4
	v_mov_b32_e32 v88, v4
	v_mov_b32_e32 v89, v4
	v_mov_b32_e32 v90, v4
	v_mov_b32_e32 v91, v4
	v_mov_b32_e32 v100, v4
	v_mov_b32_e32 v101, v4
	v_mov_b32_e32 v102, v4
	v_mov_b32_e32 v103, v4
	v_mov_b32_e32 v104, v4
	v_mov_b32_e32 v105, v4
	v_mov_b32_e32 v106, v4
	v_mov_b32_e32 v107, v4
	v_mov_b32_e32 v116, v4
	v_mov_b32_e32 v117, v4
	v_mov_b32_e32 v118, v4
	v_mov_b32_e32 v119, v4
	v_mov_b32_e32 v120, v4
	v_mov_b32_e32 v121, v4
	v_mov_b32_e32 v122, v4
	v_mov_b32_e32 v123, v4
	v_mov_b32_e32 v124, v4
	v_mov_b32_e32 v125, v4
	v_mov_b32_e32 v126, v4
	v_mov_b32_e32 v127, v4
	v_mov_b32_e32 v128, v4
	v_mov_b32_e32 v129, v4
	v_mov_b32_e32 v130, v4
	v_mov_b32_e32 v131, v4
	.p2align	6
